# MLA: tile barrier + K/V LDS writes before the PV MFMAs, next tile's first K fragments read and next-next tile's global loads issued right after the barrier
# baseline (speedup 1.0000x reference)
.LBB0_1370:
	v_exp_f32_e32 v96, v96
	v_exp_f32_e32 v97, v97
	v_exp_f32_e32 v98, v98
	v_exp_f32_e32 v99, v99
	v_exp_f32_e32 v100, v100
	v_exp_f32_e32 v101, v101
	v_exp_f32_e32 v102, v102
	v_exp_f32_e32 v103, v103
	v_cvt_pk_bf16_f32 v96, v96, v97
	v_cvt_pk_bf16_f32 v97, v98, v99
	v_cvt_pk_bf16_f32 v98, v100, v101
	v_cvt_pk_bf16_f32 v99, v102, v103
	v_exp_f32_e32 v88, v88
	v_exp_f32_e32 v89, v89
	v_exp_f32_e32 v90, v90
	v_exp_f32_e32 v91, v91
	v_exp_f32_e32 v100, v92
	v_exp_f32_e32 v101, v93
	v_exp_f32_e32 v102, v94
	v_exp_f32_e32 v103, v95
	v_mov_b64_e32 v[136:137], s[14:15]
	v_mov_b64_e32 v[134:135], s[12:13]
	v_mov_b32_e32 v109, v108
	v_mov_b32_e32 v110, v108
	v_mov_b32_e32 v111, v108
	s_waitcnt lgkmcnt(1)
	v_mov_b32_e32 v105, v104
	v_mov_b32_e32 v106, v104
	s_waitcnt lgkmcnt(0)
	v_mov_b32_e32 v107, v104
	v_cvt_pk_bf16_f32 v88, v88, v89
	v_cvt_pk_bf16_f32 v89, v90, v91
	v_cvt_pk_bf16_f32 v90, v100, v101
	v_cvt_pk_bf16_f32 v91, v102, v103
	v_mfma_f32_16x16x32_bf16 v[100:103], v[68:71], v[96:99], v[108:111]
	v_exp_f32_e32 v113, v76
	v_exp_f32_e32 v115, v81
	v_exp_f32_e32 v117, v82
	v_mfma_f32_16x16x32_bf16 v[122:125], v[68:71], v[88:91], v[104:107]
	v_exp_f32_e32 v68, v77
	v_exp_f32_e32 v69, v78
	v_exp_f32_e32 v70, v79
	v_mfma_f32_16x16x32_bf16 v[76:79], v[64:67], v[96:99], v[108:111]
	v_exp_f32_e32 v71, v80
	v_cvt_pk_bf16_f32 v80, v113, v68
	v_cvt_pk_bf16_f32 v81, v69, v70
	v_mfma_f32_16x16x32_bf16 v[126:129], v[64:67], v[88:91], v[104:107]
	v_exp_f32_e32 v64, v83
	v_cvt_pk_bf16_f32 v82, v71, v115
	s_waitcnt vmcnt(1)
	ds_write_b128 v121, v[32:35] offset:14336
	v_mfma_f32_16x16x32_bf16 v[130:133], v[52:55], v[96:99], v[108:111]
	v_cvt_pk_bf16_f32 v83, v117, v64
	v_lshlrev_b32_e32 v144, 1, v116
	v_mfma_f32_16x16x32_bf16 v[138:141], v[52:55], v[88:91], v[104:107]
	v_exp_f32_e32 v52, v56
	v_exp_f32_e32 v53, v57
	v_exp_f32_e32 v54, v58
	v_exp_f32_e32 v55, v59
	v_exp_f32_e32 v56, v60
	v_exp_f32_e32 v57, v61
	v_exp_f32_e32 v58, v62
	v_exp_f32_e32 v59, v63
	v_mfma_f32_16x16x32_bf16 v[92:95], v[84:87], v[96:99], v[108:111]
	v_mfma_f32_16x16x32_bf16 v[84:87], v[84:87], v[88:91], v[104:107]
	v_mfma_f32_16x16x32_bf16 v[96:99], v[134:137], v[96:99], v[108:111]
	v_mfma_f32_16x16x32_bf16 v[88:91], v[134:137], v[88:91], v[104:107]
	s_nop 2
	v_cvt_pk_bf16_f32 v104, v52, v53
	v_cvt_pk_bf16_f32 v105, v54, v55
	v_cvt_pk_bf16_f32 v106, v56, v57
	v_cvt_pk_bf16_f32 v107, v58, v59
	v_mfma_f32_16x16x32_bf16 v[68:71], v[48:51], v[80:83], v[92:95]
	s_nop 0
	v_mfma_f32_16x16x32_bf16 v[64:67], v[48:51], v[104:107], v[84:87]
	v_mfma_f32_16x16x32_bf16 v[60:63], v[44:47], v[80:83], v[100:103]
	v_mfma_f32_16x16x32_bf16 v[56:59], v[44:47], v[104:107], v[122:125]
	v_mfma_f32_16x16x32_bf16 v[52:55], v[40:43], v[80:83], v[76:79]
	v_mfma_f32_16x16x32_bf16 v[48:51], v[40:43], v[104:107], v[126:129]
	v_mfma_f32_16x16x32_bf16 v[44:47], v[36:39], v[80:83], v[130:133]
	v_mfma_f32_16x16x32_bf16 v[40:43], v[36:39], v[104:107], v[138:141]
	v_mfma_f32_16x16x32_bf16 v[36:39], v[134:137], v[80:83], v[96:99]
	v_mfma_f32_16x16x32_bf16 v[32:35], v[134:137], v[104:107], v[88:91]
	s_and_saveexec_b64 s[26:27], s[6:7]
	v_lshl_add_u32 v76, v171, 1, v144
	ds_write_b128 v76, v[28:31] offset:14336
	s_or_b64 exec, exec, s[26:27]
	s_lshl_b32 s26, s43, 8
	v_mov_b32_e32 v115, v145
	s_addk_i32 s26, 0x7800
	s_mov_b32 s27, 1
	v_lshl_add_u64 v[160:161], s[0:1], 0, v[114:115]
	v_add_u32_e32 v177, 0x80, v119
	v_add_u32_e32 v178, 0x80, v120
	v_add_u32_e32 v179, 0x80, v118
	v_lshlrev_b32_e32 v180, 1, v112
	v_mov_b32_e32 v203, 0
	v_mov_b32_e32 v210, v179
	v_mov_b32_e32 v211, 0
	v_mov_b32_e32 v214, 0x800
	v_lshlrev_b64 v[212:213], 11, v[210:211]
	v_lshlrev_b64 v[210:211], 6, v[210:211]
	v_lshl_add_u64 v[210:211], v[152:153], 0, v[210:211]
	v_lshl_add_u64 v[212:213], v[150:151], 0, v[212:213]
	v_lshl_add_u64 v[210:211], v[210:211], 0, s[24:25]
	v_cndmask_b32_e64 v205, v211, v213, s[4:5]
	v_cndmask_b32_e64 v204, v210, v212, s[4:5]
	v_mov_b32_e32 v206, 64
	v_cndmask_b32_e64 v206, v206, v214, s[4:5]
	v_mov_b32_e32 v210, v177
	v_mov_b32_e32 v211, 0
	v_lshlrev_b64 v[212:213], 11, v[210:211]
	v_lshlrev_b64 v[210:211], 6, v[210:211]
	v_lshl_add_u64 v[212:213], v[156:157], 0, v[212:213]
	v_lshl_add_u64 v[210:211], v[154:155], 0, v[210:211]
	v_cndmask_b32_e64 v209, v211, v213, s[8:9]
	v_cndmask_b32_e64 v208, v210, v212, s[8:9]
	v_mov_b32_e32 v207, 64
	v_cndmask_b32_e64 v207, v207, v214, s[8:9]
	v_mov_b32_e32 v210, v178
	v_mov_b32_e32 v211, 0
	v_lshlrev_b64 v[210:211], 11, v[210:211]
	v_lshl_add_u64 v[216:217], v[160:161], 0, v[210:211]
	v_xor_b32_e32 v218, 0x80000000, v159
	v_xor_b32_e32 v222, 0x80000000, v158
	v_mov_b32_e32 v219, v218
	v_mov_b32_e32 v220, v218
	v_mov_b32_e32 v221, v218
	v_mov_b32_e32 v223, v222
	v_mov_b32_e32 v224, v222
	v_mov_b32_e32 v225, v222
	v_mov_b64_e32 v[228:229], s[12:13]
	v_mov_b64_e32 v[230:231], s[14:15]
	s_waitcnt vmcnt(0)
	ds_write_b128 v174, v[72:75] offset:38912
	s_waitcnt lgkmcnt(0)
	s_barrier
	v_add_u32_e32 v244, 0x3800, v175
	ds_read_b128 v[236:239], v244
	ds_read_b128 v[240:243], v244 offset:64
	s_cmp_lt_u32 s27, 31
	s_cselect_b32 s43, s42, s26
	s_lshl_b32 s98, s27, 6
	s_add_i32 s98, s98, s43
	s_addk_i32 s98, 0xffc0
	s_lshl_b32 s100, s98, 11
	s_mov_b32 s101, 0
	v_mul_u32_u24_e32 v202, s98, v206
	v_lshl_add_u64 v[72:73], v[204:205], 0, v[202:203]
	global_load_dwordx4 v[72:75], v[72:73], off
	s_and_saveexec_b64 s[0:1], s[6:7]
	s_cbranch_execz .Lmla_p1376
	v_mul_u32_u24_e32 v202, s98, v207
	v_lshl_add_u64 v[28:29], v[208:209], 0, v[202:203]
	global_load_dwordx4 v[28:31], v[28:29], off
.Lmla_p1376:
	s_or_b64 exec, exec, s[0:1]
	v_lshl_add_u64 v[232:233], v[216:217], 0, s[100:101]
	global_load_dwordx4 v[232:235], v[232:233], off offset:128
	s_branch .LBB0_1374
.LBB0_1374:
	s_and_b32 s99, s27, 1
	s_mul_i32 s99, s99, 0x3800
	v_add_u32_e32 v124, s99, v175
	s_and_b32 s0, s27, 1
	s_mul_i32 s1, s0, 0x3800
	s_waitcnt lgkmcnt(1)
	v_mfma_f32_16x16x32_bf16 v[92:95], v[236:239], v[20:23], v[218:221]
	ds_read_b128 v[96:99], v124 offset:3584
	ds_read_b128 v[100:103], v124 offset:128
	ds_read_b128 v[108:111], v124 offset:7168
	ds_read_b128 v[112:115], v124 offset:7232
	ds_read_b128 v[120:123], v124 offset:10752
	ds_read_b128 v[182:185], v124 offset:7296
	v_mfma_f32_16x16x32_bf16 v[76:79], v[236:239], v[24:27], v[222:225]
	s_mul_i32 s1, s0, 0x2800
	s_waitcnt lgkmcnt(5)
	v_mfma_f32_16x16x32_bf16 v[104:107], v[96:99], v[20:23], v[218:221]
	v_mfma_f32_16x16x32_bf16 v[96:99], v[96:99], v[24:27], v[222:225]
	s_waitcnt lgkmcnt(3)
	v_mfma_f32_16x16x32_bf16 v[116:119], v[108:111], v[20:23], v[218:221]
	v_mfma_f32_16x16x32_bf16 v[108:111], v[108:111], v[24:27], v[222:225]
	s_waitcnt lgkmcnt(1)
	v_mfma_f32_16x16x32_bf16 v[80:83], v[120:123], v[20:23], v[218:221]
	v_mfma_f32_16x16x32_bf16 v[84:87], v[120:123], v[24:27], v[222:225]
	v_mfma_f32_16x16x32_bf16 v[92:95], v[240:243], v[12:15], v[92:95]
	v_mfma_f32_16x16x32_bf16 v[76:79], v[240:243], v[16:19], v[76:79]
	ds_read_b128 v[88:91], v124 offset:3648
	ds_read_b128 v[120:123], v124 offset:3712
	s_waitcnt lgkmcnt(1)
	v_mfma_f32_16x16x32_bf16 v[104:107], v[88:91], v[12:15], v[104:107]
	v_mfma_f32_16x16x32_bf16 v[88:91], v[88:91], v[16:19], v[96:99]
	s_nop 2
	ds_read_b128 v[96:99], v124 offset:10816
	ds_read_b128 v[190:193], v124 offset:10880
	s_waitcnt lgkmcnt(1)
	v_mfma_f32_16x16x32_bf16 v[194:197], v[96:99], v[12:15], v[80:83]
	s_nop 2
	v_mfma_f32_16x16x32_bf16 v[128:131], v[100:103], v[4:7], v[76:79]
	v_add_u32_e32 v82, s1, v176
	s_nop 1
	v_mfma_f32_16x16x32_bf16 v[116:119], v[112:115], v[12:15], v[116:119]
	v_mfma_f32_16x16x32_bf16 v[186:189], v[112:115], v[16:19], v[108:111]
	v_mfma_f32_16x16x32_bf16 v[198:201], v[96:99], v[16:19], v[84:87]
	ds_read_b64_tr_b16 v[124:125], v82 offset:28672
	ds_read_b64_tr_b16 v[112:113], v82 offset:28704
	ds_read_b64_tr_b16 v[108:109], v82 offset:28736
	ds_read_b64_tr_b16 v[96:97], v82 offset:28768
	ds_read_b64_tr_b16 v[126:127], v82 offset:31232
	ds_read_b64_tr_b16 v[114:115], v82 offset:31264
	ds_read_b64_tr_b16 v[110:111], v82 offset:31296
	ds_read_b64_tr_b16 v[98:99], v82 offset:31328
	v_mfma_f32_16x16x32_bf16 v[136:139], v[100:103], v[8:11], v[92:95]
	v_mfma_f32_16x16x32_bf16 v[132:135], v[120:123], v[4:7], v[88:91]
	s_nop 1
	ds_read_b64_tr_b16 v[92:93], v82 offset:33792
	ds_read_b64_tr_b16 v[88:89], v82 offset:33824
	ds_read_b64_tr_b16 v[84:85], v82 offset:33856
	ds_read_b64_tr_b16 v[80:81], v82 offset:33888
	ds_read_b64_tr_b16 v[94:95], v82 offset:36352
	ds_read_b64_tr_b16 v[90:91], v82 offset:36384
	ds_read_b64_tr_b16 v[86:87], v82 offset:36416
	ds_read_b64_tr_b16 v[82:83], v82 offset:36448
	v_mfma_f32_16x16x32_bf16 v[140:143], v[120:123], v[8:11], v[104:107]
	v_mfma_f32_16x16x32_bf16 v[116:119], v[182:185], v[8:11], v[116:119]
	v_mfma_f32_16x16x32_bf16 v[100:103], v[182:185], v[4:7], v[186:189]
	s_waitcnt lgkmcnt(14)
	v_mfma_f32_16x16x32_bf16 v[120:123], v[190:193], v[8:11], v[194:197]
	v_mfma_f32_16x16x32_bf16 v[104:107], v[190:193], v[4:7], v[198:201]
	v_max3_f32 v181, v136, v137, v138
	v_max3_f32 v183, v128, v129, v130
	v_max3_f32 v184, v131, v132, v133
	v_max3_f32 v181, v181, v139, v140
	v_max3_f32 v183, v183, v134, v135
	v_max3_f32 v181, v181, v141, v142
	v_max3_f32 v182, v143, v116, v117
	v_max3_f32 v184, v184, v100, v101
	v_max3_f32 v182, v182, v118, v119
	v_max3_f32 v184, v184, v102, v103
	v_max3_f32 v181, v181, v120, v121
	v_max3_f32 v182, v182, v122, v123
	v_max3_f32 v183, v183, v104, v105
	v_max3_f32 v184, v184, v106, v107
	v_max_f32_e32 v181, v181, v182
	v_max_f32_e32 v183, v183, v184
	v_max_f32_e32 v184, v181, v183
	v_cmp_lt_f32_e32 vcc, s36, v184
	s_cbranch_vccz .LBB0_1378
	v_mov_b32_e32 v182, v181
	v_mov_b32_e32 v184, v183
	s_nop 1
	v_permlane16_swap_b32_e32 v181, v182
	v_permlane16_swap_b32_e32 v183, v184
	v_max_f32_e32 v181, v181, v182
	v_max_f32_e32 v183, v183, v184
	v_mov_b32_e32 v182, v181
	v_mov_b32_e32 v184, v183
	s_nop 1
	v_permlane32_swap_b32_e32 v181, v182
	v_permlane32_swap_b32_e32 v183, v184
	v_max_f32_e32 v182, v181, v182
	v_max_f32_e32 v181, v183, v184
	v_max_f32_e32 v182, v182, v182
	v_max_f32_e32 v183, 0, v182
	v_exp_f32_e64 v182, -v183
	v_max_f32_e32 v181, v181, v181
	v_sub_f32_e32 v136, v136, v183
	v_sub_f32_e32 v137, v137, v183
	v_pk_mul_f32 v[70:71], v[70:71], v[182:183] op_sel_hi:[1,0]
	v_pk_mul_f32 v[68:69], v[68:69], v[182:183] op_sel_hi:[1,0]
	v_pk_mul_f32 v[62:63], v[62:63], v[182:183] op_sel_hi:[1,0]
	v_pk_mul_f32 v[60:61], v[60:61], v[182:183] op_sel_hi:[1,0]
	v_pk_mul_f32 v[54:55], v[54:55], v[182:183] op_sel_hi:[1,0]
	v_pk_mul_f32 v[52:53], v[52:53], v[182:183] op_sel_hi:[1,0]
	v_pk_mul_f32 v[46:47], v[46:47], v[182:183] op_sel_hi:[1,0]
	v_pk_mul_f32 v[44:45], v[44:45], v[182:183] op_sel_hi:[1,0]
	v_pk_mul_f32 v[38:39], v[38:39], v[182:183] op_sel_hi:[1,0]
	v_pk_mul_f32 v[36:37], v[36:37], v[182:183] op_sel_hi:[1,0]
	v_max_f32_e32 v182, 0, v181
	v_exp_f32_e64 v184, -v182
	v_sub_f32_e32 v138, v138, v183
	v_sub_f32_e32 v139, v139, v183
	v_sub_f32_e32 v140, v140, v183
	v_sub_f32_e32 v141, v141, v183
	v_sub_f32_e32 v142, v142, v183
	v_sub_f32_e32 v143, v143, v183
	v_sub_f32_e32 v116, v116, v183
	v_sub_f32_e32 v117, v117, v183
	v_sub_f32_e32 v118, v118, v183
	v_sub_f32_e32 v119, v119, v183
	v_sub_f32_e32 v120, v120, v183
	v_sub_f32_e32 v121, v121, v183
	v_sub_f32_e32 v122, v122, v183
	v_sub_f32_e32 v123, v123, v183
	v_pk_add_f32 v[158:159], v[158:159], v[182:183]
	v_xor_b32_e32 v218, 0x80000000, v159
	v_xor_b32_e32 v222, 0x80000000, v158
	v_mov_b32_e32 v219, v218
	v_mov_b32_e32 v220, v218
	v_mov_b32_e32 v221, v218
	v_mov_b32_e32 v223, v222
	v_mov_b32_e32 v224, v222
	v_mov_b32_e32 v225, v222
	v_sub_f32_e32 v128, v128, v182
	v_sub_f32_e32 v129, v129, v182
	v_sub_f32_e32 v130, v130, v182
	v_sub_f32_e32 v131, v131, v182
	v_sub_f32_e32 v132, v132, v182
	v_sub_f32_e32 v133, v133, v182
	v_sub_f32_e32 v134, v134, v182
	v_sub_f32_e32 v135, v135, v182
	v_sub_f32_e32 v100, v100, v182
	v_sub_f32_e32 v101, v101, v182
	v_sub_f32_e32 v102, v102, v182
	v_sub_f32_e32 v103, v103, v182
	v_sub_f32_e32 v104, v104, v182
	v_sub_f32_e32 v105, v105, v182
	v_sub_f32_e32 v106, v106, v182
	v_sub_f32_e32 v107, v107, v182
	v_pk_mul_f32 v[66:67], v[66:67], v[184:185] op_sel_hi:[1,0]
	v_pk_mul_f32 v[64:65], v[64:65], v[184:185] op_sel_hi:[1,0]
	v_pk_mul_f32 v[58:59], v[58:59], v[184:185] op_sel_hi:[1,0]
	v_pk_mul_f32 v[56:57], v[56:57], v[184:185] op_sel_hi:[1,0]
	v_pk_mul_f32 v[50:51], v[50:51], v[184:185] op_sel_hi:[1,0]
	v_pk_mul_f32 v[48:49], v[48:49], v[184:185] op_sel_hi:[1,0]
	v_pk_mul_f32 v[42:43], v[42:43], v[184:185] op_sel_hi:[1,0]
	v_pk_mul_f32 v[40:41], v[40:41], v[184:185] op_sel_hi:[1,0]
	v_pk_mul_f32 v[34:35], v[34:35], v[184:185] op_sel_hi:[1,0]
	v_pk_mul_f32 v[32:33], v[32:33], v[184:185] op_sel_hi:[1,0]
.LBB0_1378:
	v_exp_f32_e32 v136, v136
	v_exp_f32_e32 v137, v137
	v_exp_f32_e32 v138, v138
	v_exp_f32_e32 v139, v139
	v_exp_f32_e32 v140, v140
	v_exp_f32_e32 v141, v141
	v_exp_f32_e32 v142, v142
	v_exp_f32_e32 v143, v143
	v_exp_f32_e32 v128, v128
	v_exp_f32_e32 v129, v129
	v_exp_f32_e32 v130, v130
	v_exp_f32_e32 v131, v131
	v_exp_f32_e32 v132, v132
	v_exp_f32_e32 v133, v133
	v_exp_f32_e32 v134, v134
	v_exp_f32_e32 v135, v135
	v_cvt_pk_bf16_f32 v136, v136, v137
	v_cvt_pk_bf16_f32 v137, v138, v139
	v_cvt_pk_bf16_f32 v138, v140, v141
	v_cvt_pk_bf16_f32 v139, v142, v143
	v_cvt_pk_bf16_f32 v128, v128, v129
	v_cvt_pk_bf16_f32 v129, v130, v131
	v_cvt_pk_bf16_f32 v130, v132, v133
	v_cvt_pk_bf16_f32 v131, v134, v135
	s_xor_b32 s43, s0, 1
	s_mul_i32 s46, s43, 0x3800
	v_lshlrev_b32_e32 v244, 1, v170
	v_add3_u32 v244, s46, v244, v180
	v_lshlrev_b32_e32 v245, 1, v171
	v_add3_u32 v245, s46, v245, v144
	s_mulk_i32 s43, 0x2800
	v_add_u32_e32 v202, s43, v174
	s_waitcnt vmcnt(0)
	ds_write_b128 v244, v[72:75]
	s_and_saveexec_b64 s[100:101], s[6:7]
	ds_write_b128 v245, v[28:31]
	s_or_b64 exec, exec, s[100:101]
	ds_write_b128 v202, v[232:235] offset:28672
	s_waitcnt lgkmcnt(0)
	s_barrier
	s_add_i32 s27, s27, 1
	v_add_u32_e32 v244, s46, v175
	ds_read_b128 v[236:239], v244
	ds_read_b128 v[240:243], v244 offset:64
	s_cmp_lg_u32 s27, 35
	s_cbranch_scc0 .Lmla_nold
	s_cmp_lt_u32 s27, 31
	s_cselect_b32 s43, s42, s26
	s_lshl_b32 s98, s27, 6
	s_add_i32 s98, s98, s43
	s_addk_i32 s98, 0xffc0
	s_lshl_b32 s100, s98, 11
	s_mov_b32 s101, 0
	v_mul_u32_u24_e32 v202, s98, v206
	v_lshl_add_u64 v[72:73], v[204:205], 0, v[202:203]
	global_load_dwordx4 v[72:75], v[72:73], off
	s_and_saveexec_b64 s[0:1], s[6:7]
	s_cbranch_execz .LBB0_1376
	v_mul_u32_u24_e32 v202, s98, v207
	v_lshl_add_u64 v[28:29], v[208:209], 0, v[202:203]
	global_load_dwordx4 v[28:31], v[28:29], off

.Lmla_nold:
	v_mfma_f32_16x16x32_bf16 v[60:63], v[112:115], v[136:139], v[60:63]
	v_exp_f32_e32 v116, v116
	v_mfma_f32_16x16x32_bf16 v[56:59], v[112:115], v[128:131], v[56:59]
	v_exp_f32_e32 v112, v117
	v_exp_f32_e32 v113, v118
	v_exp_f32_e32 v114, v119
	v_exp_f32_e32 v115, v120
	v_exp_f32_e32 v117, v121
	v_mfma_f32_16x16x32_bf16 v[52:55], v[108:111], v[136:139], v[52:55]
	v_exp_f32_e32 v118, v122
	v_mfma_f32_16x16x32_bf16 v[48:51], v[108:111], v[128:131], v[48:51]
	v_cvt_pk_bf16_f32 v108, v116, v112
	v_cvt_pk_bf16_f32 v109, v113, v114
	v_cvt_pk_bf16_f32 v110, v115, v117
	v_exp_f32_e32 v111, v123
	v_mfma_f32_16x16x32_bf16 v[44:47], v[96:99], v[136:139], v[44:47]
	v_cvt_pk_bf16_f32 v111, v118, v111
	v_mfma_f32_16x16x32_bf16 v[40:43], v[96:99], v[128:131], v[40:43]
	v_exp_f32_e32 v96, v100
	v_exp_f32_e32 v97, v101
	v_exp_f32_e32 v98, v102
	v_exp_f32_e32 v99, v103
	v_exp_f32_e32 v100, v104
	v_exp_f32_e32 v101, v105
	v_exp_f32_e32 v102, v106
	v_exp_f32_e32 v103, v107
	v_mfma_f32_16x16x32_bf16 v[68:71], v[124:127], v[136:139], v[68:71]
	v_cvt_pk_bf16_f32 v96, v96, v97
	v_cvt_pk_bf16_f32 v97, v98, v99
	v_cvt_pk_bf16_f32 v98, v100, v101
	v_mfma_f32_16x16x32_bf16 v[64:67], v[124:127], v[128:131], v[64:67]
	v_cvt_pk_bf16_f32 v99, v102, v103
	v_mfma_f32_16x16x32_bf16 v[36:39], v[228:231], v[136:139], v[36:39]
	v_mfma_f32_16x16x32_bf16 v[32:35], v[228:231], v[128:131], v[32:35]
	v_mfma_f32_16x16x32_bf16 v[68:71], v[92:95], v[108:111], v[68:71]
	v_mfma_f32_16x16x32_bf16 v[64:67], v[92:95], v[96:99], v[64:67]
	v_mfma_f32_16x16x32_bf16 v[60:63], v[88:91], v[108:111], v[60:63]
	v_mfma_f32_16x16x32_bf16 v[56:59], v[88:91], v[96:99], v[56:59]
	v_mfma_f32_16x16x32_bf16 v[52:55], v[84:87], v[108:111], v[52:55]
	v_mfma_f32_16x16x32_bf16 v[48:51], v[84:87], v[96:99], v[48:51]
	v_mfma_f32_16x16x32_bf16 v[44:47], v[80:83], v[108:111], v[44:47]
	v_mfma_f32_16x16x32_bf16 v[40:43], v[80:83], v[96:99], v[40:43]
	v_mfma_f32_16x16x32_bf16 v[36:39], v[228:231], v[108:111], v[36:39]
	v_mfma_f32_16x16x32_bf16 v[32:35], v[228:231], v[96:99], v[32:35]
	s_cmp_lg_u32 s27, 35
	s_cbranch_scc1 .LBB0_1374
